# gate2 silu moved from B1 GEMM epilogue into hand-written combine phase (2 items per iteration, 12 loads in flight)
# speedup vs baseline: 1.0026x; 1.0026x over previous
.LBB0_716:
	s_lshl_b32 s55, s66, 10
	s_cmp_lt_u32 s24, 4
	s_cselect_b64 s[62:63], -1, 0
	s_cmp_gt_u32 s24, 3
	s_cselect_b64 s[64:65], -1, 0
	s_and_b32 s12, s24, -4
	s_cmp_lg_u32 s12, 8
	s_cselect_b64 s[12:13], -1, 0
	s_and_b64 s[66:67], s[64:65], s[12:13]
	v_lshl_add_u32 v220, s18, 8, v1
	s_mov_b64 s[12:13], -1
	s_and_b64 vcc, exec, s[66:67]
	s_cbranch_vccz .LBB0_750
	v_add_u32_e32 v130, s55, v239
	ds_read2_b32 v[146:147], v130 offset1:16
	ds_read2_b32 v[142:143], v130 offset0:32 offset1:48
	ds_read2_b32 v[138:139], v130 offset0:128 offset1:144
	ds_read2_b32 v[134:135], v130 offset0:160 offset1:176
	s_ashr_i32 s12, s24, 2
	s_cmp_eq_u32 s12, 9
	s_cselect_b64 s[66:67], -1, 0
	s_cmp_lg_u32 s12, 9
	s_waitcnt lgkmcnt(0)
	v_mov_b32_e32 v144, v147
	v_mov_b32_e32 v140, v143
	v_mov_b32_e32 v136, v139
	v_mov_b32_e32 v130, v135
	v_pk_mul_f32 v[150:151], v[128:129], v[146:147] op_sel_hi:[1,0]
	v_pk_mul_f32 v[154:155], v[126:127], v[146:147] op_sel_hi:[1,0]
	v_pk_mul_f32 v[152:153], v[124:125], v[146:147] op_sel_hi:[1,0]
	v_pk_mul_f32 v[156:157], v[122:123], v[146:147] op_sel_hi:[1,0]
	s_cbranch_scc1 .LBB0_719
	v_mul_f32_e32 v131, 0xbfb8aa3b, v154
	v_exp_f32_e32 v131, v131
	v_mul_f32_e32 v132, 0xbfb8aa3b, v156
	v_exp_f32_e32 v135, v132
	v_mul_f32_e32 v133, 0xbfb8aa3b, v155
	v_add_f32_e32 v131, 1.0, v131
	v_rcp_f32_e32 v132, v131
	v_add_f32_e32 v131, 1.0, v135
	v_mul_f32_e32 v135, 0xbfb8aa3b, v150
	v_exp_f32_e32 v135, v135
	v_mul_f32_e32 v137, 0xbfb8aa3b, v152
	v_exp_f32_e32 v133, v133
	v_exp_f32_e32 v137, v137
	v_add_f32_e32 v135, 1.0, v135
	v_rcp_f32_e32 v148, v131
	v_add_f32_e32 v131, 1.0, v133
	v_rcp_f32_e32 v158, v135
	v_add_f32_e32 v135, 1.0, v137
	v_mul_f32_e32 v137, 0xbfb8aa3b, v151
	v_rcp_f32_e32 v133, v131
	v_mul_f32_e32 v131, 0xbfb8aa3b, v157
	v_exp_f32_e32 v137, v137
	v_mul_f32_e32 v139, 0xbfb8aa3b, v153
	v_exp_f32_e32 v131, v131
	v_exp_f32_e32 v139, v139
	v_rcp_f32_e32 v160, v135
	v_add_f32_e32 v135, 1.0, v137
	v_add_f32_e32 v131, 1.0, v131
	v_rcp_f32_e32 v159, v135
	v_add_f32_e32 v135, 1.0, v139
	v_rcp_f32_e32 v161, v135
	v_rcp_f32_e32 v149, v131
	v_pk_mul_f32 v[150:151], v[150:151], v[158:159]
	v_pk_mul_f32 v[154:155], v[154:155], v[132:133]
	v_pk_mul_f32 v[152:153], v[152:153], v[160:161]
	v_pk_mul_f32 v[156:157], v[156:157], v[148:149]

.LBB0_1122:
	s_cmp_lt_i32 s34, 10
	s_cselect_b64 s[4:5], -1, 0
	s_and_b64 s[6:7], s[4:5], s[0:1]
	s_andn2_b64 vcc, exec, s[6:7]
	s_cbranch_vccnz .LBB0_1133
	s_waitcnt vmcnt(0) lgkmcnt(0)
	s_lshl_b32 s0, s44, 9
	v_or_b32_e32 v22, s0, v0
	s_lshl_b32 s14, s30, 9
	s_mov_b32 s15, 0x400000
	s_add_u32 s10, s38, 0x2400000
	s_addc_u32 s11, s39, 0
	s_add_u32 s12, s36, 0x4000000
	s_addc_u32 s13, s37, 0
	s_add_u32 s16, s38, 0x4000000
	s_addc_u32 s17, s39, 0
	s_add_u32 s18, s38, 0x10000000
	s_addc_u32 s19, s39, 0
	v_mov_b32_e32 v1, 0xf149f2ca
.Lp9_loop:
	v_cmp_gt_u32_e32 vcc, s15, v22
	s_and_saveexec_b64 s[8:9], vcc
	s_cbranch_execz .Lp9_exit
	v_add_u32_e32 v23, s14, v22
	v_cmp_gt_u32_e64 s[20:21], s15, v23
	v_min_u32_e32 v75, 0x3fffff, v23
	v_lshlrev_b32_e32 v24, 4, v22
	v_lshlrev_b32_e32 v25, 4, v75
	v_and_b32_e32 v76, -16, v22
	v_and_b32_e32 v77, -16, v75
	v_lshrrev_b32_e32 v78, 4, v22
	v_lshrrev_b32_e32 v80, 4, v75
	v_and_b32_e32 v79, 15, v22
	v_and_b32_e32 v81, 15, v75
	v_mul_u32_u24_e32 v78, 0x300, v78
	v_mul_u32_u24_e32 v80, 0x300, v80
	v_lshl_add_u32 v78, v79, 4, v78
	v_lshl_add_u32 v80, v81, 4, v80
	global_load_dwordx4 v[26:29], v76, s[10:11]
	global_load_dwordx4 v[30:33], v24, s[12:13] nt
	global_load_dwordx4 v[34:37], v78, s[18:19] nt
	global_load_dwordx4 v[38:41], v78, s[18:19] offset:256 nt
	global_load_dwordx4 v[42:45], v78, s[18:19] offset:512 nt
	global_load_dwordx4 v[46:49], v24, s[36:37] nt
	global_load_dwordx4 v[50:53], v77, s[10:11]
	global_load_dwordx4 v[54:57], v25, s[12:13] nt
	global_load_dwordx4 v[58:61], v80, s[18:19] nt
	global_load_dwordx4 v[62:65], v80, s[18:19] offset:256 nt
	global_load_dwordx4 v[66:69], v80, s[18:19] offset:512 nt
	global_load_dwordx4 v[70:73], v25, s[36:37] nt
	s_waitcnt vmcnt(6)
	v_bfe_u32 v84, v22, 15, 6
	v_cmp_lt_u32_e64 s[0:1], 0, v84
	v_cmp_lt_u32_e64 s[4:5], 1, v84
	v_cmp_lt_u32_e64 s[22:23], 2, v84
	v_lshlrev_b32_e32 v100, 16, v46
	v_and_b32_e32 v101, 0xffff0000, v46
	v_lshlrev_b32_e32 v102, 16, v47
	v_and_b32_e32 v103, 0xffff0000, v47
	v_lshlrev_b32_e32 v104, 16, v48
	v_and_b32_e32 v105, 0xffff0000, v48
	v_lshlrev_b32_e32 v106, 16, v49
	v_and_b32_e32 v107, 0xffff0000, v49
	v_cndmask_b32_e64 v85, v1, v26, s[0:1]
	v_cndmask_b32_e64 v86, v1, v27, s[4:5]
	v_cndmask_b32_e64 v87, v1, v28, s[22:23]
	v_max_f32_e32 v88, v29, v29
	v_max_f32_e32 v89, v87, v87
	v_max_f32_e32 v89, v89, v88
	v_max3_f32 v89, v85, v86, v89
	v_sub_f32_e32 v85, v85, v89
	v_sub_f32_e32 v86, v86, v89
	v_sub_f32_e32 v87, v87, v89
	v_sub_f32_e32 v88, v29, v89
	v_mul_f32_e32 v108, 0xbfb8aa3b, v100
	v_mul_f32_e32 v109, 0xbfb8aa3b, v101
	v_mul_f32_e32 v110, 0xbfb8aa3b, v102
	v_mul_f32_e32 v111, 0xbfb8aa3b, v103
	v_mul_f32_e32 v112, 0xbfb8aa3b, v104
	v_mul_f32_e32 v113, 0xbfb8aa3b, v105
	v_mul_f32_e32 v114, 0xbfb8aa3b, v106
	v_mul_f32_e32 v115, 0xbfb8aa3b, v107
	v_exp_f32_e32 v85, v85
	v_exp_f32_e32 v86, v86
	v_exp_f32_e32 v87, v87
	v_exp_f32_e32 v88, v88
	v_exp_f32_e32 v108, v108
	v_exp_f32_e32 v109, v109
	v_exp_f32_e32 v110, v110
	v_exp_f32_e32 v111, v111
	v_exp_f32_e32 v112, v112
	v_exp_f32_e32 v113, v113
	v_exp_f32_e32 v114, v114
	v_exp_f32_e32 v115, v115
	v_cndmask_b32_e64 v34, 0, v34, s[0:1]
	v_cndmask_b32_e64 v35, 0, v35, s[0:1]
	v_cndmask_b32_e64 v36, 0, v36, s[0:1]
	v_cndmask_b32_e64 v37, 0, v37, s[0:1]
	v_cndmask_b32_e64 v38, 0, v38, s[4:5]
	v_cndmask_b32_e64 v39, 0, v39, s[4:5]
	v_cndmask_b32_e64 v40, 0, v40, s[4:5]
	v_cndmask_b32_e64 v41, 0, v41, s[4:5]
	v_cndmask_b32_e64 v42, 0, v42, s[22:23]
	v_cndmask_b32_e64 v43, 0, v43, s[22:23]
	v_cndmask_b32_e64 v44, 0, v44, s[22:23]
	v_cndmask_b32_e64 v45, 0, v45, s[22:23]
	v_add_f32_e32 v90, v85, v86
	v_add_f32_e32 v91, v87, v88
	v_add_f32_e32 v90, v90, v91
	v_add_f32_e32 v108, 1.0, v108
	v_add_f32_e32 v109, 1.0, v109
	v_add_f32_e32 v110, 1.0, v110
	v_add_f32_e32 v111, 1.0, v111
	v_add_f32_e32 v112, 1.0, v112
	v_add_f32_e32 v113, 1.0, v113
	v_add_f32_e32 v114, 1.0, v114
	v_add_f32_e32 v115, 1.0, v115
	v_rcp_f32_e32 v90, v90
	v_rcp_f32_e32 v108, v108
	v_rcp_f32_e32 v109, v109
	v_rcp_f32_e32 v110, v110
	v_rcp_f32_e32 v111, v111
	v_rcp_f32_e32 v112, v112
	v_rcp_f32_e32 v113, v113
	v_rcp_f32_e32 v114, v114
	v_rcp_f32_e32 v115, v115
	v_lshlrev_b32_e32 v92, 16, v38
	v_lshlrev_b32_e32 v93, 16, v42
	v_lshlrev_b32_e32 v94, 16, v34
	v_lshlrev_b32_e32 v95, 16, v30
	v_mul_f32_e32 v92, v86, v92
	v_mul_f32_e32 v93, v87, v93
	v_fma_f32 v92, v85, v94, v92
	v_fma_f32 v93, v88, v95, v93
	v_add_f32_e32 v116, v92, v93
	v_and_b32_e32 v92, 0xffff0000, v38
	v_and_b32_e32 v93, 0xffff0000, v42
	v_and_b32_e32 v94, 0xffff0000, v34
	v_and_b32_e32 v95, 0xffff0000, v30
	v_mul_f32_e32 v92, v86, v92
	v_mul_f32_e32 v93, v87, v93
	v_fma_f32 v92, v85, v94, v92
	v_fma_f32 v93, v88, v95, v93
	v_add_f32_e32 v117, v92, v93
	v_lshlrev_b32_e32 v92, 16, v39
	v_lshlrev_b32_e32 v93, 16, v43
	v_lshlrev_b32_e32 v94, 16, v35
	v_lshlrev_b32_e32 v95, 16, v31
	v_mul_f32_e32 v92, v86, v92
	v_mul_f32_e32 v93, v87, v93
	v_fma_f32 v92, v85, v94, v92
	v_fma_f32 v93, v88, v95, v93
	v_add_f32_e32 v118, v92, v93
	v_and_b32_e32 v92, 0xffff0000, v39
	v_and_b32_e32 v93, 0xffff0000, v43
	v_and_b32_e32 v94, 0xffff0000, v35
	v_and_b32_e32 v95, 0xffff0000, v31
	v_mul_f32_e32 v92, v86, v92
	v_mul_f32_e32 v93, v87, v93
	v_fma_f32 v92, v85, v94, v92
	v_fma_f32 v93, v88, v95, v93
	v_add_f32_e32 v119, v92, v93
	v_lshlrev_b32_e32 v92, 16, v40
	v_lshlrev_b32_e32 v93, 16, v44
	v_lshlrev_b32_e32 v94, 16, v36
	v_lshlrev_b32_e32 v95, 16, v32
	v_mul_f32_e32 v92, v86, v92
	v_mul_f32_e32 v93, v87, v93
	v_fma_f32 v92, v85, v94, v92
	v_fma_f32 v93, v88, v95, v93
	v_add_f32_e32 v120, v92, v93
	v_and_b32_e32 v92, 0xffff0000, v40
	v_and_b32_e32 v93, 0xffff0000, v44
	v_and_b32_e32 v94, 0xffff0000, v36
	v_and_b32_e32 v95, 0xffff0000, v32
	v_mul_f32_e32 v92, v86, v92
	v_mul_f32_e32 v93, v87, v93
	v_fma_f32 v92, v85, v94, v92
	v_fma_f32 v93, v88, v95, v93
	v_add_f32_e32 v121, v92, v93
	v_lshlrev_b32_e32 v92, 16, v41
	v_lshlrev_b32_e32 v93, 16, v45
	v_lshlrev_b32_e32 v94, 16, v37
	v_lshlrev_b32_e32 v95, 16, v33
	v_mul_f32_e32 v92, v86, v92
	v_mul_f32_e32 v93, v87, v93
	v_fma_f32 v92, v85, v94, v92
	v_fma_f32 v93, v88, v95, v93
	v_add_f32_e32 v122, v92, v93
	v_and_b32_e32 v92, 0xffff0000, v41
	v_and_b32_e32 v93, 0xffff0000, v45
	v_and_b32_e32 v94, 0xffff0000, v37
	v_and_b32_e32 v95, 0xffff0000, v33
	v_mul_f32_e32 v92, v86, v92
	v_mul_f32_e32 v93, v87, v93
	v_fma_f32 v92, v85, v94, v92
	v_fma_f32 v93, v88, v95, v93
	v_add_f32_e32 v123, v92, v93
	v_mul_f32_e32 v100, v100, v108
	v_mul_f32_e32 v101, v101, v109
	v_mul_f32_e32 v102, v102, v110
	v_mul_f32_e32 v103, v103, v111
	v_mul_f32_e32 v104, v104, v112
	v_mul_f32_e32 v105, v105, v113
	v_mul_f32_e32 v106, v106, v114
	v_mul_f32_e32 v107, v107, v115
	v_mul_f32_e32 v116, v90, v116
	v_mul_f32_e32 v117, v90, v117
	v_mul_f32_e32 v118, v90, v118
	v_mul_f32_e32 v119, v90, v119
	v_mul_f32_e32 v120, v90, v120
	v_mul_f32_e32 v121, v90, v121
	v_mul_f32_e32 v122, v90, v122
	v_mul_f32_e32 v123, v90, v123
	v_mul_f32_e32 v116, v116, v100
	v_mul_f32_e32 v117, v117, v101
	v_mul_f32_e32 v118, v118, v102
	v_mul_f32_e32 v119, v119, v103
	v_mul_f32_e32 v120, v120, v104
	v_mul_f32_e32 v121, v121, v105
	v_mul_f32_e32 v122, v122, v106
	v_mul_f32_e32 v123, v123, v107
	v_cvt_pk_bf16_f32 v124, v116, v117
	v_cvt_pk_bf16_f32 v125, v118, v119
	v_cvt_pk_bf16_f32 v126, v120, v121
	v_cvt_pk_bf16_f32 v127, v122, v123
	global_store_dwordx4 v24, v[124:127], s[16:17]
	s_waitcnt vmcnt(1)
	s_and_b64 exec, exec, s[20:21]
	s_cbranch_execz .Lp9_skipb
	v_bfe_u32 v84, v23, 15, 6
	v_cmp_lt_u32_e64 s[0:1], 0, v84
	v_cmp_lt_u32_e64 s[4:5], 1, v84
	v_cmp_lt_u32_e64 s[22:23], 2, v84
	v_lshlrev_b32_e32 v100, 16, v70
	v_and_b32_e32 v101, 0xffff0000, v70
	v_lshlrev_b32_e32 v102, 16, v71
	v_and_b32_e32 v103, 0xffff0000, v71
	v_lshlrev_b32_e32 v104, 16, v72
	v_and_b32_e32 v105, 0xffff0000, v72
	v_lshlrev_b32_e32 v106, 16, v73
	v_and_b32_e32 v107, 0xffff0000, v73
	v_cndmask_b32_e64 v85, v1, v50, s[0:1]
	v_cndmask_b32_e64 v86, v1, v51, s[4:5]
	v_cndmask_b32_e64 v87, v1, v52, s[22:23]
	v_max_f32_e32 v88, v53, v53
	v_max_f32_e32 v89, v87, v87
	v_max_f32_e32 v89, v89, v88
	v_max3_f32 v89, v85, v86, v89
	v_sub_f32_e32 v85, v85, v89
	v_sub_f32_e32 v86, v86, v89
	v_sub_f32_e32 v87, v87, v89
	v_sub_f32_e32 v88, v53, v89
	v_mul_f32_e32 v108, 0xbfb8aa3b, v100
	v_mul_f32_e32 v109, 0xbfb8aa3b, v101
	v_mul_f32_e32 v110, 0xbfb8aa3b, v102
	v_mul_f32_e32 v111, 0xbfb8aa3b, v103
	v_mul_f32_e32 v112, 0xbfb8aa3b, v104
	v_mul_f32_e32 v113, 0xbfb8aa3b, v105
	v_mul_f32_e32 v114, 0xbfb8aa3b, v106
	v_mul_f32_e32 v115, 0xbfb8aa3b, v107
	v_exp_f32_e32 v85, v85
	v_exp_f32_e32 v86, v86
	v_exp_f32_e32 v87, v87
	v_exp_f32_e32 v88, v88
	v_exp_f32_e32 v108, v108
	v_exp_f32_e32 v109, v109
	v_exp_f32_e32 v110, v110
	v_exp_f32_e32 v111, v111
	v_exp_f32_e32 v112, v112
	v_exp_f32_e32 v113, v113
	v_exp_f32_e32 v114, v114
	v_exp_f32_e32 v115, v115
	v_cndmask_b32_e64 v58, 0, v58, s[0:1]
	v_cndmask_b32_e64 v59, 0, v59, s[0:1]
	v_cndmask_b32_e64 v60, 0, v60, s[0:1]
	v_cndmask_b32_e64 v61, 0, v61, s[0:1]
	v_cndmask_b32_e64 v62, 0, v62, s[4:5]
	v_cndmask_b32_e64 v63, 0, v63, s[4:5]
	v_cndmask_b32_e64 v64, 0, v64, s[4:5]
	v_cndmask_b32_e64 v65, 0, v65, s[4:5]
	v_cndmask_b32_e64 v66, 0, v66, s[22:23]
	v_cndmask_b32_e64 v67, 0, v67, s[22:23]
	v_cndmask_b32_e64 v68, 0, v68, s[22:23]
	v_cndmask_b32_e64 v69, 0, v69, s[22:23]
	v_add_f32_e32 v90, v85, v86
	v_add_f32_e32 v91, v87, v88
	v_add_f32_e32 v90, v90, v91
	v_add_f32_e32 v108, 1.0, v108
	v_add_f32_e32 v109, 1.0, v109
	v_add_f32_e32 v110, 1.0, v110
	v_add_f32_e32 v111, 1.0, v111
	v_add_f32_e32 v112, 1.0, v112
	v_add_f32_e32 v113, 1.0, v113
	v_add_f32_e32 v114, 1.0, v114
	v_add_f32_e32 v115, 1.0, v115
	v_rcp_f32_e32 v90, v90
	v_rcp_f32_e32 v108, v108
	v_rcp_f32_e32 v109, v109
	v_rcp_f32_e32 v110, v110
	v_rcp_f32_e32 v111, v111
	v_rcp_f32_e32 v112, v112
	v_rcp_f32_e32 v113, v113
	v_rcp_f32_e32 v114, v114
	v_rcp_f32_e32 v115, v115
	v_lshlrev_b32_e32 v92, 16, v62
	v_lshlrev_b32_e32 v93, 16, v66
	v_lshlrev_b32_e32 v94, 16, v58
	v_lshlrev_b32_e32 v95, 16, v54
	v_mul_f32_e32 v92, v86, v92
	v_mul_f32_e32 v93, v87, v93
	v_fma_f32 v92, v85, v94, v92
	v_fma_f32 v93, v88, v95, v93
	v_add_f32_e32 v116, v92, v93
	v_and_b32_e32 v92, 0xffff0000, v62
	v_and_b32_e32 v93, 0xffff0000, v66
	v_and_b32_e32 v94, 0xffff0000, v58
	v_and_b32_e32 v95, 0xffff0000, v54
	v_mul_f32_e32 v92, v86, v92
	v_mul_f32_e32 v93, v87, v93
	v_fma_f32 v92, v85, v94, v92
	v_fma_f32 v93, v88, v95, v93
	v_add_f32_e32 v117, v92, v93
	v_lshlrev_b32_e32 v92, 16, v63
	v_lshlrev_b32_e32 v93, 16, v67
	v_lshlrev_b32_e32 v94, 16, v59
	v_lshlrev_b32_e32 v95, 16, v55
	v_mul_f32_e32 v92, v86, v92
	v_mul_f32_e32 v93, v87, v93
	v_fma_f32 v92, v85, v94, v92
	v_fma_f32 v93, v88, v95, v93
	v_add_f32_e32 v118, v92, v93
	v_and_b32_e32 v92, 0xffff0000, v63
	v_and_b32_e32 v93, 0xffff0000, v67
	v_and_b32_e32 v94, 0xffff0000, v59
	v_and_b32_e32 v95, 0xffff0000, v55
	v_mul_f32_e32 v92, v86, v92
	v_mul_f32_e32 v93, v87, v93
	v_fma_f32 v92, v85, v94, v92
	v_fma_f32 v93, v88, v95, v93
	v_add_f32_e32 v119, v92, v93
	v_lshlrev_b32_e32 v92, 16, v64
	v_lshlrev_b32_e32 v93, 16, v68
	v_lshlrev_b32_e32 v94, 16, v60
	v_lshlrev_b32_e32 v95, 16, v56
	v_mul_f32_e32 v92, v86, v92
	v_mul_f32_e32 v93, v87, v93
	v_fma_f32 v92, v85, v94, v92
	v_fma_f32 v93, v88, v95, v93
	v_add_f32_e32 v120, v92, v93
	v_and_b32_e32 v92, 0xffff0000, v64
	v_and_b32_e32 v93, 0xffff0000, v68
	v_and_b32_e32 v94, 0xffff0000, v60
	v_and_b32_e32 v95, 0xffff0000, v56
	v_mul_f32_e32 v92, v86, v92
	v_mul_f32_e32 v93, v87, v93
	v_fma_f32 v92, v85, v94, v92
	v_fma_f32 v93, v88, v95, v93
	v_add_f32_e32 v121, v92, v93
	v_lshlrev_b32_e32 v92, 16, v65
	v_lshlrev_b32_e32 v93, 16, v69
	v_lshlrev_b32_e32 v94, 16, v61
	v_lshlrev_b32_e32 v95, 16, v57
	v_mul_f32_e32 v92, v86, v92
	v_mul_f32_e32 v93, v87, v93
	v_fma_f32 v92, v85, v94, v92
	v_fma_f32 v93, v88, v95, v93
	v_add_f32_e32 v122, v92, v93
	v_and_b32_e32 v92, 0xffff0000, v65
	v_and_b32_e32 v93, 0xffff0000, v69
	v_and_b32_e32 v94, 0xffff0000, v61
	v_and_b32_e32 v95, 0xffff0000, v57
	v_mul_f32_e32 v92, v86, v92
	v_mul_f32_e32 v93, v87, v93
	v_fma_f32 v92, v85, v94, v92
	v_fma_f32 v93, v88, v95, v93
	v_add_f32_e32 v123, v92, v93
	v_mul_f32_e32 v100, v100, v108
	v_mul_f32_e32 v101, v101, v109
	v_mul_f32_e32 v102, v102, v110
	v_mul_f32_e32 v103, v103, v111
	v_mul_f32_e32 v104, v104, v112
	v_mul_f32_e32 v105, v105, v113
	v_mul_f32_e32 v106, v106, v114
	v_mul_f32_e32 v107, v107, v115
	v_mul_f32_e32 v116, v90, v116
	v_mul_f32_e32 v117, v90, v117
	v_mul_f32_e32 v118, v90, v118
	v_mul_f32_e32 v119, v90, v119
	v_mul_f32_e32 v120, v90, v120
	v_mul_f32_e32 v121, v90, v121
	v_mul_f32_e32 v122, v90, v122
	v_mul_f32_e32 v123, v90, v123
	v_mul_f32_e32 v116, v116, v100
	v_mul_f32_e32 v117, v117, v101
	v_mul_f32_e32 v118, v118, v102
	v_mul_f32_e32 v119, v119, v103
	v_mul_f32_e32 v120, v120, v104
	v_mul_f32_e32 v121, v121, v105
	v_mul_f32_e32 v122, v122, v106
	v_mul_f32_e32 v123, v123, v107
	v_cvt_pk_bf16_f32 v128, v116, v117
	v_cvt_pk_bf16_f32 v129, v118, v119
	v_cvt_pk_bf16_f32 v130, v120, v121
	v_cvt_pk_bf16_f32 v131, v122, v123
	global_store_dwordx4 v25, v[128:131], s[16:17]
.Lp9_skipb:
	s_or_b64 exec, exec, s[8:9]
	v_add_u32_e32 v22, s14, v23
	s_branch .Lp9_loop
